# adds: MLA P.V V-fragment reads double-buffered in the 16 freed VGPRs, first batch read ahead (group B across the barrier, group A under softmax); no lgkmcnt(0) before the step barrier
# baseline (speedup 1.0000x reference)
.Lkvdma_skip:
	s_mov_b32 s70, s36
	s_cmp_eq_u32 s57, 2
	s_cselect_b64 s[42:43], -1, 0
	s_xor_b64 s[74:75], s[80:81], -1
	s_or_b64 s[42:43], s[74:75], s[42:43]
	s_and_b64 vcc, exec, s[42:43]
	s_cbranch_vccnz .LBB0_148
	s_setprio 1
	v_lshl_add_u32 v210, s37, 14, v218
	ds_read_b64_tr_b16 v[80:81], v210 offset:0x200
	ds_read_b64_tr_b16 v[82:83], v210 offset:0xa00
	ds_read_b64_tr_b16 v[84:85], v210 offset:0x1200
	ds_read_b64_tr_b16 v[86:87], v210 offset:0x1a00
	ds_read_b64_tr_b16 v[88:89], v210 offset:0x2200
	ds_read_b64_tr_b16 v[90:91], v210 offset:0x2a00
	ds_read_b64_tr_b16 v[92:93], v210 offset:0x3200
	ds_read_b64_tr_b16 v[94:95], v210 offset:0x3a00
	s_waitcnt lgkmcnt(8)
	s_nop 0
	v_mfma_f32_32x32x16_bf16 v[32:47], v[76:79], v[154:157], v[32:47]
	ds_read_b64_tr_b16 v[154:155], v210 offset:0x400
	ds_read_b64_tr_b16 v[156:157], v210 offset:0xc00
	v_mfma_f32_32x32x16_bf16 v[32:47], v[72:75], v[158:161], v[32:47]
	ds_read_b64_tr_b16 v[158:159], v210 offset:0x1400
	ds_read_b64_tr_b16 v[160:161], v210 offset:0x1c00
	v_mfma_f32_32x32x16_bf16 v[32:47], v[68:71], v[162:165], v[32:47]
	ds_read_b64_tr_b16 v[162:163], v210 offset:0x2400
	ds_read_b64_tr_b16 v[164:165], v210 offset:0x2c00
	v_mfma_f32_32x32x16_bf16 v[32:47], v[64:67], v[206:209], v[32:47]
	ds_read_b64_tr_b16 v[206:207], v210 offset:0x3400
	ds_read_b64_tr_b16 v[208:209], v210 offset:0x3c00
	s_waitcnt lgkmcnt(8)
	v_mfma_f32_32x32x16_bf16 v[48:63], v[76:79], v[80:83], v[48:63]
	ds_read_b64_tr_b16 v[80:81], v210 offset:0x600
	ds_read_b64_tr_b16 v[82:83], v210 offset:0xe00
	v_mfma_f32_32x32x16_bf16 v[48:63], v[72:75], v[84:87], v[48:63]
	ds_read_b64_tr_b16 v[84:85], v210 offset:0x1600
	ds_read_b64_tr_b16 v[86:87], v210 offset:0x1e00
	v_mfma_f32_32x32x16_bf16 v[48:63], v[68:71], v[88:91], v[48:63]
	ds_read_b64_tr_b16 v[88:89], v210 offset:0x2600
	ds_read_b64_tr_b16 v[90:91], v210 offset:0x2e00
	v_mfma_f32_32x32x16_bf16 v[48:63], v[64:67], v[92:95], v[48:63]
	ds_read_b64_tr_b16 v[92:93], v210 offset:0x3600
	ds_read_b64_tr_b16 v[94:95], v210 offset:0x3e00
	s_waitcnt lgkmcnt(8)
	v_mfma_f32_32x32x16_bf16 v[16:31], v[76:79], v[154:157], v[16:31]
	v_mfma_f32_32x32x16_bf16 v[16:31], v[72:75], v[158:161], v[16:31]
	v_mfma_f32_32x32x16_bf16 v[16:31], v[68:71], v[162:165], v[16:31]
	v_mfma_f32_32x32x16_bf16 v[16:31], v[64:67], v[206:209], v[16:31]
	s_waitcnt lgkmcnt(0)
	v_mfma_f32_32x32x16_bf16 v[0:15], v[76:79], v[80:83], v[0:15]
	v_mfma_f32_32x32x16_bf16 v[0:15], v[72:75], v[84:87], v[0:15]
	v_mfma_f32_32x32x16_bf16 v[0:15], v[68:71], v[88:91], v[0:15]
	v_mfma_f32_32x32x16_bf16 v[0:15], v[64:67], v[92:95], v[0:15]
	s_setprio 0
.LBB0_148:
	s_add_i32 s36, s57, -2
	s_and_b32 s74, s36, 1
	s_lshl_b32 s36, s74, 14
	s_lshl_b32 s42, s74, 13
	s_add_i32 s42, s42, 0x14000
	v_add3_u32 v210, s36, v222, v221
	v_add3_u32 v211, s36, v223, v221
	v_add3_u32 v212, s36, v224, v221
	v_add3_u32 v213, s36, v225, v221
	ds_read_b128 v[240:243], v210 offset:49152
	ds_read_b128 v[244:247], v211 offset:49152
	ds_read_b128 v[248:251], v212 offset:49152
	ds_read_b128 v[236:239], v213 offset:49152
	ds_read_b128 v[64:67], v210 offset:49280
	ds_read_b128 v[68:71], v211 offset:49280
	ds_read_b128 v[72:75], v212 offset:49280
	ds_read_b128 v[76:79], v213 offset:49280
	v_add3_u32 v234, s42, v227, v226
	v_add3_u32 v235, s42, v228, v226
	s_waitcnt lgkmcnt(7)
	v_mfma_f32_32x32x16_bf16 v[80:95], v[240:243], v[98:101], 0
	ds_read_b128 v[240:243], v234
	s_waitcnt lgkmcnt(7)
	v_mfma_f32_32x32x16_bf16 v[80:95], v[244:247], v[102:105], v[80:95]
	ds_read_b128 v[244:247], v235
	v_add3_u32 v234, s42, v229, v226
	v_add3_u32 v235, s42, v230, v226
	s_waitcnt lgkmcnt(7)
	v_mfma_f32_32x32x16_bf16 v[80:95], v[248:251], v[106:109], v[80:95]
	ds_read_b128 v[248:251], v234
	s_waitcnt lgkmcnt(7)
	v_mfma_f32_32x32x16_bf16 v[80:95], v[236:239], v[110:113], v[80:95]
	ds_read_b128 v[236:239], v235
	s_waitcnt lgkmcnt(7)
	v_mfma_f32_32x32x16_bf16 v[80:95], v[64:67], v[114:117], v[80:95]
	ds_read_b128 v[64:67], v210 offset:57344
	s_waitcnt lgkmcnt(7)
	v_mfma_f32_32x32x16_bf16 v[80:95], v[68:71], v[118:121], v[80:95]
	s_waitcnt lgkmcnt(6)
	v_mfma_f32_32x32x16_bf16 v[80:95], v[72:75], v[122:125], v[80:95]
	s_waitcnt lgkmcnt(5)
	v_mfma_f32_32x32x16_bf16 v[80:95], v[76:79], v[126:129], v[80:95]
	s_waitcnt lgkmcnt(4)
	v_mfma_f32_32x32x16_bf16 v[80:95], v[240:243], v[130:133], v[80:95]
	ds_read_b128 v[240:243], v211 offset:57344
	s_waitcnt lgkmcnt(4)
	v_mfma_f32_32x32x16_bf16 v[80:95], v[244:247], v[138:141], v[80:95]
	ds_read_b128 v[244:247], v212 offset:57344
	s_waitcnt lgkmcnt(4)
	v_mfma_f32_32x32x16_bf16 v[80:95], v[248:251], v[134:137], v[80:95]
	ds_read_b128 v[248:251], v213 offset:57344
	s_waitcnt lgkmcnt(4)
	v_mfma_f32_32x32x16_bf16 v[80:95], v[236:239], v[142:145], v[80:95]
	ds_read_b128 v[236:239], v210 offset:57472
	s_waitcnt lgkmcnt(4)
	v_mfma_f32_32x32x16_bf16 v[64:79], v[64:67], v[98:101], 0
	s_waitcnt lgkmcnt(3)
	v_mfma_f32_32x32x16_bf16 v[64:79], v[240:243], v[102:105], v[64:79]
	ds_read_b128 v[240:243], v211 offset:57472
	s_waitcnt lgkmcnt(3)
	v_mfma_f32_32x32x16_bf16 v[64:79], v[244:247], v[106:109], v[64:79]
	ds_read_b128 v[244:247], v212 offset:57472
	v_add3_u32 v210, s42, v227, v226
	s_waitcnt lgkmcnt(3)
	v_mfma_f32_32x32x16_bf16 v[64:79], v[248:251], v[110:113], v[64:79]
	ds_read_b128 v[248:251], v213 offset:57472
	v_add3_u32 v211, s42, v228, v226
	s_waitcnt lgkmcnt(3)
	v_mfma_f32_32x32x16_bf16 v[64:79], v[236:239], v[114:117], v[64:79]
	ds_read_b128 v[236:239], v210 offset:4096
	v_add3_u32 v212, s42, v229, v226
	s_waitcnt lgkmcnt(3)
	v_mfma_f32_32x32x16_bf16 v[64:79], v[240:243], v[118:121], v[64:79]
	ds_read_b128 v[240:243], v211 offset:4096
	v_add3_u32 v213, s42, v230, v226
	s_waitcnt lgkmcnt(3)
	v_mfma_f32_32x32x16_bf16 v[64:79], v[244:247], v[122:125], v[64:79]
	ds_read_b128 v[244:247], v212 offset:4096
	s_waitcnt lgkmcnt(3)
	v_mfma_f32_32x32x16_bf16 v[64:79], v[248:251], v[126:129], v[64:79]
	ds_read_b128 v[248:251], v213 offset:4096
	s_waitcnt lgkmcnt(3)
	v_mfma_f32_32x32x16_bf16 v[64:79], v[236:239], v[130:133], v[64:79]
	s_waitcnt lgkmcnt(2)
	v_mfma_f32_32x32x16_bf16 v[64:79], v[240:243], v[138:141], v[64:79]
	s_waitcnt lgkmcnt(1)
	v_mfma_f32_32x32x16_bf16 v[64:79], v[244:247], v[134:137], v[64:79]
	s_waitcnt lgkmcnt(0)
	v_mfma_f32_32x32x16_bf16 v[64:79], v[248:251], v[142:145], v[64:79]
	s_and_b64 vcc, exec, s[80:81]
	s_cbranch_vccnz .Lpv2_askip
	v_lshl_add_u32 v216, s70, 14, v218
	ds_read_b64_tr_b16 v[154:155], v216 offset:0x0
	ds_read_b64_tr_b16 v[156:157], v216 offset:0x800
	ds_read_b64_tr_b16 v[158:159], v216 offset:0x1000
	ds_read_b64_tr_b16 v[160:161], v216 offset:0x1800
	ds_read_b64_tr_b16 v[162:163], v216 offset:0x2000
	ds_read_b64_tr_b16 v[164:165], v216 offset:0x2800
	ds_read_b64_tr_b16 v[206:207], v216 offset:0x3000
	ds_read_b64_tr_b16 v[208:209], v216 offset:0x3800
.Lpv2_askip:
	s_add_i32 s36, s8, 63
	s_cmp_le_i32 s36, s2
	s_cselect_b64 s[36:37], -1, 0
	s_cmp_gt_i32 s8, s55
	s_cselect_b64 s[42:43], -1, 0
	s_and_b64 s[36:37], s[36:37], s[42:43]
	s_and_b64 vcc, exec, s[36:37]
	s_cbranch_vccnz .LBB0_150
	v_add_u32_e32 v210, s69, v231
	v_cmp_gt_u32_e32 vcc, s66, v210
	v_add_u32_e32 v211, 0xffefffe0, v210
	s_nop 0
	v_cndmask_b32_e32 v80, v214, v80, vcc
	v_cmp_lt_u32_e32 vcc, s67, v211
	v_add_u32_e32 v211, 0xffefffff, v210
	s_nop 0
	v_cndmask_b32_e32 v64, v214, v64, vcc
	v_cmp_lt_u32_e32 vcc, s67, v211
	v_add_u32_e32 v211, 0xffefffdf, v210
	s_nop 0
	v_cndmask_b32_e32 v81, v214, v81, vcc
	v_cmp_lt_u32_e32 vcc, s67, v211
	v_add_u32_e32 v211, 0xffeffffe, v210
	s_nop 0
	v_cndmask_b32_e32 v65, v214, v65, vcc
	v_cmp_lt_u32_e32 vcc, s67, v211
	v_add_u32_e32 v211, 0xffefffde, v210
	s_nop 0
	v_cndmask_b32_e32 v82, v214, v82, vcc
	v_cmp_lt_u32_e32 vcc, s67, v211
	v_add_u32_e32 v211, 0xffeffffd, v210
	s_nop 0
	v_cndmask_b32_e32 v66, v214, v66, vcc
	v_cmp_lt_u32_e32 vcc, s67, v211
	v_add_u32_e32 v211, 0xffefffdd, v210
	s_nop 0
	v_cndmask_b32_e32 v83, v214, v83, vcc
	v_cmp_lt_u32_e32 vcc, s67, v211
	v_add_u32_e32 v211, 0xffeffff8, v210
	s_nop 0
	v_cndmask_b32_e32 v67, v214, v67, vcc
	v_cmp_lt_u32_e32 vcc, s67, v211
	v_add_u32_e32 v211, 0xffefffd8, v210
	s_nop 0
	v_cndmask_b32_e32 v84, v214, v84, vcc
	v_cmp_lt_u32_e32 vcc, s67, v211
	v_add_u32_e32 v211, 0xffeffff7, v210
	s_nop 0
	v_cndmask_b32_e32 v68, v214, v68, vcc
	v_cmp_lt_u32_e32 vcc, s67, v211
	v_add_u32_e32 v211, 0xffefffd7, v210
	s_nop 0
	v_cndmask_b32_e32 v85, v214, v85, vcc
	v_cmp_lt_u32_e32 vcc, s67, v211
	v_add_u32_e32 v211, 0xffeffff6, v210
	s_nop 0
	v_cndmask_b32_e32 v69, v214, v69, vcc
	v_cmp_lt_u32_e32 vcc, s67, v211
	v_add_u32_e32 v211, 0xffefffd6, v210
	s_nop 0
	v_cndmask_b32_e32 v86, v214, v86, vcc
	v_cmp_lt_u32_e32 vcc, s67, v211
	v_add_u32_e32 v211, 0xffeffff5, v210
	s_nop 0
	v_cndmask_b32_e32 v70, v214, v70, vcc
	v_cmp_lt_u32_e32 vcc, s67, v211
	v_add_u32_e32 v211, 0xffefffd5, v210
	s_nop 0
	v_cndmask_b32_e32 v87, v214, v87, vcc
	v_cmp_lt_u32_e32 vcc, s67, v211
	v_add_u32_e32 v211, 0xffeffff0, v210
	s_nop 0
	v_cndmask_b32_e32 v71, v214, v71, vcc
	v_cmp_lt_u32_e32 vcc, s67, v211
	v_add_u32_e32 v211, 0xffefffd0, v210
	s_nop 0
	v_cndmask_b32_e32 v88, v214, v88, vcc
	v_cmp_lt_u32_e32 vcc, s67, v211
	v_add_u32_e32 v211, 0xffefffef, v210
	s_nop 0
	v_cndmask_b32_e32 v72, v214, v72, vcc
	v_cmp_lt_u32_e32 vcc, s67, v211
	v_add_u32_e32 v211, 0xffefffcf, v210
	s_nop 0
	v_cndmask_b32_e32 v89, v214, v89, vcc
	v_cmp_lt_u32_e32 vcc, s67, v211
	v_add_u32_e32 v211, 0xffefffee, v210
	s_nop 0
	v_cndmask_b32_e32 v73, v214, v73, vcc
	v_cmp_lt_u32_e32 vcc, s67, v211
	v_add_u32_e32 v211, 0xffefffce, v210
	s_nop 0
	v_cndmask_b32_e32 v90, v214, v90, vcc
	v_cmp_lt_u32_e32 vcc, s67, v211
	v_add_u32_e32 v211, 0xffefffed, v210
	s_nop 0
	v_cndmask_b32_e32 v74, v214, v74, vcc
	v_cmp_lt_u32_e32 vcc, s67, v211
	v_add_u32_e32 v211, 0xffefffcd, v210
	s_nop 0
	v_cndmask_b32_e32 v91, v214, v91, vcc
	v_cmp_lt_u32_e32 vcc, s67, v211
	v_add_u32_e32 v211, 0xffefffe8, v210
	s_nop 0
	v_cndmask_b32_e32 v75, v214, v75, vcc
	v_cmp_lt_u32_e32 vcc, s67, v211
	v_add_u32_e32 v211, 0xffefffc8, v210
	s_nop 0
	v_cndmask_b32_e32 v92, v214, v92, vcc
	v_cmp_lt_u32_e32 vcc, s67, v211
	v_add_u32_e32 v211, 0xffefffe7, v210
	s_nop 0
	v_cndmask_b32_e32 v76, v214, v76, vcc
	v_cmp_lt_u32_e32 vcc, s67, v211
	v_add_u32_e32 v211, 0xffefffc7, v210
	s_nop 0
	v_cndmask_b32_e32 v93, v214, v93, vcc
	v_cmp_lt_u32_e32 vcc, s67, v211
	v_add_u32_e32 v211, 0xffefffe6, v210
	s_nop 0
	v_cndmask_b32_e32 v77, v214, v77, vcc
	v_cmp_lt_u32_e32 vcc, s67, v211
	v_add_u32_e32 v211, 0xffefffc6, v210
	s_nop 0
	v_cndmask_b32_e32 v94, v214, v94, vcc
	v_cmp_lt_u32_e32 vcc, s67, v211
	v_add_u32_e32 v211, 0xffefffe5, v210
	v_add_u32_e32 v210, 0xffefffc5, v210
	v_cndmask_b32_e32 v78, v214, v78, vcc
	v_cmp_lt_u32_e32 vcc, s67, v211
	s_nop 1
	v_cndmask_b32_e32 v95, v214, v95, vcc
	v_cmp_lt_u32_e32 vcc, s67, v210
	s_nop 1
	v_cndmask_b32_e32 v79, v214, v79, vcc

.LBB0_154:
	v_cndmask_b32_e64 v232, v235, v232, s[42:43]
	v_mul_f32_e32 v210, 0xbfb8aa3b, v232
	v_fmamk_f32 v80, v80, 0x3fb8aa3b, v210
	v_fmamk_f32 v81, v81, 0x3fb8aa3b, v210
	v_fmamk_f32 v82, v82, 0x3fb8aa3b, v210
	v_fmamk_f32 v83, v83, 0x3fb8aa3b, v210
	v_fmamk_f32 v84, v84, 0x3fb8aa3b, v210
	v_fmamk_f32 v85, v85, 0x3fb8aa3b, v210
	v_fmamk_f32 v86, v86, 0x3fb8aa3b, v210
	v_fmamk_f32 v87, v87, 0x3fb8aa3b, v210
	v_fmamk_f32 v88, v88, 0x3fb8aa3b, v210
	v_fmamk_f32 v89, v89, 0x3fb8aa3b, v210
	v_fmamk_f32 v90, v90, 0x3fb8aa3b, v210
	v_fmamk_f32 v91, v91, 0x3fb8aa3b, v210
	v_fmamk_f32 v92, v92, 0x3fb8aa3b, v210
	v_fmamk_f32 v93, v93, 0x3fb8aa3b, v210
	v_fmamk_f32 v94, v94, 0x3fb8aa3b, v210
	v_fmamk_f32 v95, v95, 0x3fb8aa3b, v210
	v_fmamk_f32 v64, v64, 0x3fb8aa3b, v210
	v_fmamk_f32 v65, v65, 0x3fb8aa3b, v210
	v_fmamk_f32 v66, v66, 0x3fb8aa3b, v210
	v_fmamk_f32 v67, v67, 0x3fb8aa3b, v210
	v_fmamk_f32 v68, v68, 0x3fb8aa3b, v210
	v_fmamk_f32 v69, v69, 0x3fb8aa3b, v210
	v_fmamk_f32 v70, v70, 0x3fb8aa3b, v210
	v_fmamk_f32 v71, v71, 0x3fb8aa3b, v210
	v_fmamk_f32 v72, v72, 0x3fb8aa3b, v210
	v_fmamk_f32 v73, v73, 0x3fb8aa3b, v210
	v_fmamk_f32 v74, v74, 0x3fb8aa3b, v210
	v_fmamk_f32 v75, v75, 0x3fb8aa3b, v210
	v_fmamk_f32 v76, v76, 0x3fb8aa3b, v210
	v_fmamk_f32 v77, v77, 0x3fb8aa3b, v210
	v_fmamk_f32 v78, v78, 0x3fb8aa3b, v210
	v_fmac_f32_e32 v210, 0x3fb8aa3b, v79
	v_exp_f32_e32 v79, v80
	v_exp_f32_e32 v211, v81
	v_exp_f32_e32 v82, v82
	v_exp_f32_e32 v83, v83
	v_exp_f32_e32 v84, v84
	v_exp_f32_e32 v212, v68
	v_add_f32_e32 v68, 0, v79
	v_exp_f32_e32 v85, v85
	v_add_f32_e32 v68, v211, v68
	v_exp_f32_e32 v86, v86
	v_add_f32_e32 v68, v82, v68
	v_exp_f32_e32 v87, v87
	v_add_f32_e32 v68, v83, v68
	v_exp_f32_e32 v88, v88
	v_add_f32_e32 v68, v84, v68
	v_exp_f32_e32 v89, v89
	v_add_f32_e32 v68, v85, v68
	v_exp_f32_e32 v90, v90
	v_add_f32_e32 v68, v86, v68
	v_exp_f32_e32 v91, v91
	v_add_f32_e32 v68, v87, v68
	v_exp_f32_e32 v92, v92
	v_add_f32_e32 v68, v88, v68
	v_exp_f32_e32 v93, v93
	v_add_f32_e32 v68, v89, v68
	v_exp_f32_e32 v94, v94
	v_add_f32_e32 v68, v90, v68
	v_exp_f32_e32 v95, v95
	v_add_f32_e32 v68, v91, v68
	v_exp_f32_e32 v64, v64
	v_add_f32_e32 v68, v92, v68
	v_exp_f32_e32 v65, v65
	v_add_f32_e32 v68, v93, v68
	v_exp_f32_e32 v66, v66
	v_add_f32_e32 v68, v94, v68
	v_exp_f32_e32 v67, v67
	v_add_f32_e32 v68, v95, v68
	v_add_f32_e32 v68, v64, v68
	v_exp_f32_e32 v213, v69
	v_add_f32_e32 v68, v65, v68
	v_exp_f32_e32 v235, v70
	v_add_f32_e32 v68, v66, v68
	v_exp_f32_e32 v71, v71
	v_add_f32_e32 v68, v67, v68
	v_exp_f32_e32 v240, v72
	v_add_f32_e32 v68, v212, v68
	v_exp_f32_e32 v241, v73
	v_add_f32_e32 v68, v213, v68
	v_exp_f32_e32 v242, v74
	v_add_f32_e32 v68, v235, v68
	v_exp_f32_e32 v243, v75
	v_add_f32_e32 v68, v71, v68
	v_exp_f32_e32 v244, v76
	v_add_f32_e32 v68, v240, v68
	v_exp_f32_e32 v245, v77
	v_add_f32_e32 v68, v241, v68
	v_exp_f32_e32 v246, v78
	v_add_f32_e32 v68, v242, v68
	v_exp_f32_e32 v210, v210
	v_add_f32_e32 v68, v243, v68
	v_add_f32_e32 v68, v244, v68
	v_add_f32_e32 v68, v245, v68
	v_add_f32_e32 v68, v246, v68
	v_add_f32_e32 v80, v210, v68
	v_mov_b32_e32 v81, v80
	v_cvt_pk_bf16_f32 v76, v79, v211
	v_cvt_pk_bf16_f32 v77, v82, v83
	v_cvt_pk_bf16_f32 v78, v84, v85
	v_cvt_pk_bf16_f32 v79, v86, v87
	v_cvt_pk_bf16_f32 v72, v88, v89
	v_cvt_pk_bf16_f32 v73, v90, v91
	v_cvt_pk_bf16_f32 v74, v92, v93
	v_cvt_pk_bf16_f32 v75, v94, v95
	v_cvt_pk_bf16_f32 v68, v64, v65
	v_cvt_pk_bf16_f32 v69, v66, v67
	v_cvt_pk_bf16_f32 v70, v212, v213
	v_cvt_pk_bf16_f32 v71, v235, v71
	v_cvt_pk_bf16_f32 v64, v240, v241
	v_cvt_pk_bf16_f32 v65, v242, v243
	v_cvt_pk_bf16_f32 v66, v244, v245
	v_cvt_pk_bf16_f32 v67, v246, v210
	s_nop 1
	v_permlane32_swap_b32_e32 v80, v81
	v_permlane32_swap_b32_e32 v76, v78
	v_permlane32_swap_b32_e32 v77, v79
	v_permlane32_swap_b32_e32 v72, v74
	v_permlane32_swap_b32_e32 v73, v75
	v_permlane32_swap_b32_e32 v68, v70
	v_permlane32_swap_b32_e32 v69, v71
	v_permlane32_swap_b32_e32 v64, v66
	v_permlane32_swap_b32_e32 v65, v67
	s_andn2_b64 vcc, exec, s[76:77]
	s_cbranch_vccnz .LBB0_156
	ds_read_b64_tr_b16 v[82:83], v216 offset:0x200
	ds_read_b64_tr_b16 v[84:85], v216 offset:0xa00
	ds_read_b64_tr_b16 v[86:87], v216 offset:0x1200
	ds_read_b64_tr_b16 v[88:89], v216 offset:0x1a00
	ds_read_b64_tr_b16 v[90:91], v216 offset:0x2200
	ds_read_b64_tr_b16 v[92:93], v216 offset:0x2a00
	ds_read_b64_tr_b16 v[210:211], v216 offset:0x3200
	ds_read_b64_tr_b16 v[212:213], v216 offset:0x3a00
	s_waitcnt lgkmcnt(8)
	s_nop 0
	v_mfma_f32_32x32x16_bf16 v[32:47], v[76:79], v[154:157], v[32:47]
	ds_read_b64_tr_b16 v[154:155], v216 offset:0x400
	ds_read_b64_tr_b16 v[156:157], v216 offset:0xc00
	v_mfma_f32_32x32x16_bf16 v[32:47], v[72:75], v[158:161], v[32:47]
	ds_read_b64_tr_b16 v[158:159], v216 offset:0x1400
	ds_read_b64_tr_b16 v[160:161], v216 offset:0x1c00
	v_mfma_f32_32x32x16_bf16 v[32:47], v[68:71], v[162:165], v[32:47]
	ds_read_b64_tr_b16 v[162:163], v216 offset:0x2400
	ds_read_b64_tr_b16 v[164:165], v216 offset:0x2c00
	v_mfma_f32_32x32x16_bf16 v[32:47], v[64:67], v[206:209], v[32:47]
	ds_read_b64_tr_b16 v[206:207], v216 offset:0x3400
	ds_read_b64_tr_b16 v[208:209], v216 offset:0x3c00
	s_waitcnt lgkmcnt(8)
	v_mfma_f32_32x32x16_bf16 v[48:63], v[76:79], v[82:85], v[48:63]
	ds_read_b64_tr_b16 v[82:83], v216 offset:0x600
	ds_read_b64_tr_b16 v[84:85], v216 offset:0xe00
	v_mfma_f32_32x32x16_bf16 v[48:63], v[72:75], v[86:89], v[48:63]
	ds_read_b64_tr_b16 v[86:87], v216 offset:0x1600
	ds_read_b64_tr_b16 v[88:89], v216 offset:0x1e00
	v_mfma_f32_32x32x16_bf16 v[48:63], v[68:71], v[90:93], v[48:63]
	ds_read_b64_tr_b16 v[90:91], v216 offset:0x2600
	ds_read_b64_tr_b16 v[92:93], v216 offset:0x2e00
	v_mfma_f32_32x32x16_bf16 v[48:63], v[64:67], v[210:213], v[48:63]
	ds_read_b64_tr_b16 v[210:211], v216 offset:0x3600
	ds_read_b64_tr_b16 v[212:213], v216 offset:0x3e00
	s_waitcnt lgkmcnt(8)
	v_mfma_f32_32x32x16_bf16 v[16:31], v[76:79], v[154:157], v[16:31]
	v_mfma_f32_32x32x16_bf16 v[16:31], v[72:75], v[158:161], v[16:31]
	v_mfma_f32_32x32x16_bf16 v[16:31], v[68:71], v[162:165], v[16:31]
	v_mfma_f32_32x32x16_bf16 v[16:31], v[64:67], v[206:209], v[16:31]
	s_waitcnt lgkmcnt(0)
	v_mfma_f32_32x32x16_bf16 v[0:15], v[76:79], v[82:85], v[0:15]
	v_mfma_f32_32x32x16_bf16 v[0:15], v[72:75], v[86:89], v[0:15]
	v_mfma_f32_32x32x16_bf16 v[0:15], v[68:71], v[90:93], v[0:15]
	v_mfma_f32_32x32x16_bf16 v[0:15], v[64:67], v[210:213], v[0:15]
.LBB0_156:
	s_add_i32 s36, s70, 1
	s_cmp_lg_u32 s70, 2
	s_cselect_b32 s36, s36, 0
	s_add_i32 s37, s57, -1
	s_cmp_ge_u32 s37, s33
	s_cbranch_scc1 .LBB0_159
	s_waitcnt vmcnt(0)
	s_and_b64 vcc, exec, s[80:81]
	s_cbranch_vccz .Lpv2_bskip
	v_lshl_add_u32 v210, s70, 14, v218
	ds_read_b64_tr_b16 v[154:155], v210 offset:0x0
	ds_read_b64_tr_b16 v[156:157], v210 offset:0x800
	ds_read_b64_tr_b16 v[158:159], v210 offset:0x1000
	ds_read_b64_tr_b16 v[160:161], v210 offset:0x1800
	ds_read_b64_tr_b16 v[162:163], v210 offset:0x2000
	ds_read_b64_tr_b16 v[164:165], v210 offset:0x2800
	ds_read_b64_tr_b16 v[206:207], v210 offset:0x3000
	ds_read_b64_tr_b16 v[208:209], v210 offset:0x3800
.Lpv2_bskip:
.LBB0_159:
	s_add_i32 s57, s57, 1
	v_add_f32_e32 v80, v80, v81
	s_ashr_i32 m0, s100, 7
	s_sub_i32 s69, s69, m0
	s_add_i32 s8, s8, m0
	s_add_i32 s37, s63, s57
	s_mul_i32 s42, s100, 24
	s_mov_b32 s43, s101
	v_fmac_f32_e32 v80, v233, v234
	s_cmp_eq_u32 s37, 2
	s_barrier
	s_cbranch_scc1 .LBB0_161
	s_mov_b32 s37, s70
	v_mov_b32_e32 v233, v80
	s_branch .LBB0_146
